# attention static priority raise at level 3 instead of 1 (timing-only)
# speedup vs baseline: 1.0081x; 1.0081x over previous
; DI int bidx() { int t = __builtin_amdgcn_readfirstlane((int)(blockIdx.x * 2 + (threadIdx.x >> 8))); asm volatile("" : "+s"(t)); return t; }
; DI int gdim() { int t = gridDim.x * 2; asm volatile("" : "+s"(t)); return t; }
; DI void phase_attn(KargPtr p, unsigned char* smem) {
;     for (int idx = bidx(); idx < 6144; idx += gdim()) {
;         if (idx < 4096) {
;             const int j = idx >> 9, g = (idx >> 7) & 3, rem = idx & 127, bh = ((rem & 63) + 13 * j) & 63;
;             const int qb = 31 - 4 * j - ((j & 1) ? 3 - g : g);
;             const int type = ((rem >> 6) + j) & 1;
;             if (type == 0) attn_item<0>(p, bh >> 3, bh & 7, qb, smem);
;             else attn_item<1>(p, bh >> 3, bh & 7, qb, smem);
;         } else {
;             const int j = idx - 4096; const int qb = 31 - (j >> 6), bh = j & 63;
;             attn_item<2>(p, bh >> 3, bh & 7, qb, smem);
;         }
;     }
; }
.LBB0_562:
	s_and_b64 vcc, exec, s[4:5]
	s_cbranch_vccz .LBB0_631
	s_cmp_lg_u32 s3, 0
	s_cbranch_scc1 .Lattn_noprio
	s_setprio 3
